# v80 + MLA progress-flag poll issued early at the loop latch (first check uses the pre-issued LDS read)
# speedup vs baseline: 1.0071x; 1.0040x over previous
; DI void phase_attn_mla(const Params& P, bf16_t* og, unsigned char* smem, int L, int G) {
;     ...
;     for (int j = 0; j <= jhi; ++j) {
;       const int key0 = j * 64, cb = j & 1;
;       __syncthreads();
.Lmy_mla_chk:
	s_waitcnt lgkmcnt(0)
	v_cmp_gt_u32_e32 vcc, s26, v251
	s_cbranch_vccz .Lmy_mla_go
	s_add_i32 s99, s99, 1
	s_cmp_lt_u32 s99, 0x40000
	s_cbranch_scc1 .Lmy_mla_spin

; DI void phase_attn_mla(const Params& P, bf16_t* og, unsigned char* smem, int L, int G) {
;     ...
;     for (int j = 0; j <= jhi; ++j) {
;       const int key0 = j * 64, cb = j & 1;
;       __syncthreads();
;       if (j < jhi) kv96x8_store(R, sK + (cb ^ 1) * KVB96, sVt + (cb ^ 1) * KVB96, tid);
;       if (j + 1 < jhi) kv96x8_fetch(R, knb, krb, vb, key0 + 128, tid);
;       __builtin_amdgcn_sched_barrier(0);
;       if (key0 <= t0 + 31) {
;         auto mf = [&](int kk) { return key0 + kk <= t; };
;         if (key0 + 63 > t0) attn_step<96, true, 0>(sK + cb * KVB96, sVt + cb * KVB96, qf, o0, o1, m, l, sc, mf, lane, s, 0.f);
;         else attn_step<96, false, 0>(sK + cb * KVB96, sVt + cb * KVB96, qf, o0, o1, m, l, sc, mf, lane, s, 0.f);
;       }
;     }
.LBB0_791:
	s_or_b64 exec, exec, s[22:23]
	s_add_i32 s14, s14, 64
	s_cmp_eq_u32 s26, s19
	s_cbranch_scc1 .LBB0_771
	ds_read_b32 v251, v250
	s_mov_b32 s26, s27
	s_branch .LBB0_779
